# MLA attention: group-B waves raise priority during their PV block (on top of pipelined QK reads)
# speedup vs baseline: 1.0068x; 1.0058x over previous
.LBB0_146:
	s_mov_b32 s70, s36
	s_cmp_eq_u32 s69, 0
	s_cselect_b64 s[42:43], -1, 0
	s_xor_b64 s[74:75], s[80:81], -1
	s_or_b64 s[42:43], s[74:75], s[42:43]
	s_and_b64 vcc, exec, s[42:43]
	s_cbranch_vccnz .LBB0_148
	s_setprio 1
	v_lshl_add_u32 v210, s37, 14, v218
	ds_read_b64_tr_b16 v[80:81], v210 offset:0
	ds_read_b64_tr_b16 v[82:83], v210 offset:0x800
	ds_read_b64_tr_b16 v[84:85], v210 offset:0x1000
	ds_read_b64_tr_b16 v[86:87], v210 offset:0x1800
	ds_read_b64_tr_b16 v[88:89], v210 offset:0x2000
	ds_read_b64_tr_b16 v[90:91], v210 offset:0x2800
	ds_read_b64_tr_b16 v[92:93], v210 offset:0x3000
	ds_read_b64_tr_b16 v[94:95], v210 offset:0x3800
	s_waitcnt lgkmcnt(0)
	s_nop 0
	v_mfma_f32_32x32x16_bf16 v[32:47], v[76:79], v[80:83], v[32:47]
	ds_read_b64_tr_b16 v[80:81], v210 offset:0x200
	ds_read_b64_tr_b16 v[82:83], v210 offset:0xa00
	v_mfma_f32_32x32x16_bf16 v[32:47], v[72:75], v[84:87], v[32:47]
	ds_read_b64_tr_b16 v[84:85], v210 offset:0x1200
	ds_read_b64_tr_b16 v[86:87], v210 offset:0x1a00
	v_mfma_f32_32x32x16_bf16 v[32:47], v[68:71], v[88:91], v[32:47]
	ds_read_b64_tr_b16 v[88:89], v210 offset:0x2200
	ds_read_b64_tr_b16 v[90:91], v210 offset:0x2a00
	v_mfma_f32_32x32x16_bf16 v[32:47], v[64:67], v[92:95], v[32:47]
	ds_read_b64_tr_b16 v[92:93], v210 offset:0x3200
	ds_read_b64_tr_b16 v[94:95], v210 offset:0x3a00
	s_waitcnt lgkmcnt(0)
	v_mfma_f32_32x32x16_bf16 v[48:63], v[76:79], v[80:83], v[48:63]
	ds_read_b64_tr_b16 v[80:81], v210 offset:0x400
	ds_read_b64_tr_b16 v[82:83], v210 offset:0xc00
	v_mfma_f32_32x32x16_bf16 v[48:63], v[72:75], v[84:87], v[48:63]
	ds_read_b64_tr_b16 v[84:85], v210 offset:0x1400
	ds_read_b64_tr_b16 v[86:87], v210 offset:0x1c00
	v_mfma_f32_32x32x16_bf16 v[48:63], v[68:71], v[88:91], v[48:63]
	ds_read_b64_tr_b16 v[88:89], v210 offset:0x2400
	ds_read_b64_tr_b16 v[90:91], v210 offset:0x2c00
	v_mfma_f32_32x32x16_bf16 v[48:63], v[64:67], v[92:95], v[48:63]
	ds_read_b64_tr_b16 v[92:93], v210 offset:0x3400
	ds_read_b64_tr_b16 v[94:95], v210 offset:0x3c00
	s_waitcnt lgkmcnt(0)
	v_mfma_f32_32x32x16_bf16 v[16:31], v[76:79], v[80:83], v[16:31]
	ds_read_b64_tr_b16 v[80:81], v210 offset:0x600
	ds_read_b64_tr_b16 v[82:83], v210 offset:0xe00
	v_mfma_f32_32x32x16_bf16 v[16:31], v[72:75], v[84:87], v[16:31]
	ds_read_b64_tr_b16 v[84:85], v210 offset:0x1600
	ds_read_b64_tr_b16 v[86:87], v210 offset:0x1e00
	v_mfma_f32_32x32x16_bf16 v[16:31], v[68:71], v[88:91], v[16:31]
	ds_read_b64_tr_b16 v[88:89], v210 offset:0x2600
	ds_read_b64_tr_b16 v[90:91], v210 offset:0x2e00
	v_mfma_f32_32x32x16_bf16 v[16:31], v[64:67], v[92:95], v[16:31]
	ds_read_b64_tr_b16 v[92:93], v210 offset:0x3600
	ds_read_b64_tr_b16 v[94:95], v210 offset:0x3e00
	s_waitcnt lgkmcnt(0)
	v_mfma_f32_32x32x16_bf16 v[0:15], v[76:79], v[80:83], v[0:15]
	v_mfma_f32_32x32x16_bf16 v[0:15], v[72:75], v[84:87], v[0:15]
	v_mfma_f32_32x32x16_bf16 v[0:15], v[68:71], v[88:91], v[0:15]
	v_mfma_f32_32x32x16_bf16 v[0:15], v[64:67], v[92:95], v[0:15]
	s_setprio 0
